# P0 MoE weight conversion in units of 4 tiles per wave: own first unit, then units claimed from an atomic counter (dynamic balance across waves / XCDs); first barrier on the short protocol
# speedup vs baseline: 1.0393x; 1.0119x over previous
.LBB0_57:
	s_or_b64 exec, exec, s[72:73]
	v_accvgpr_read_b32 v92, a1
	s_nop 0
	v_readfirstlane_b32 s40, v92
	s_mov_b32 s44, s40
	s_add_i32 s40, s40, 0x1801
	s_cmpk_lg_u32 s80, 0x800
	s_cselect_b32 s40, 0xc000, s40
	s_mov_b32 s0, s40
	v_cmp_gt_i32_e32 vcc, s0, v92
	s_and_saveexec_b64 s[0:1], vcc
	s_cbranch_execz .LBB0_63
	s_movk_i32 s3, 0x7fff
	v_cmp_lt_i32_e64 s[4:5], s3, v92
	s_and_saveexec_b64 s[6:7], s[4:5]
	s_xor_b64 s[4:5], exec, s[6:7]
	s_cbranch_execz .LBB0_60
	v_add_u32_e32 v0, 0xffff8000, v92
	v_lshrrev_b32_e32 v2, 9, v0
	v_lshlrev_b32_e32 v0, 6, v92
	v_and_b32_e32 v1, 0x3c0, v0
	v_lshlrev_b32_e32 v0, 2, v92
	v_and_b32_e32 v0, 0x7c0, v0
	v_mov_b32_e32 v3, 0
	v_readlane_b32 s8, v126, 2
	v_lshrrev_b32_e32 v6, 4, v83
	v_lshlrev_b64 v[4:5], 23, v[2:3]
	v_readlane_b32 s10, v126, 4
	v_readlane_b32 s11, v126, 5
	v_or_b32_e32 v6, v0, v6
	v_lshlrev_b32_e32 v6, 12, v6
	v_lshl_add_u64 v[4:5], s[10:11], 0, v[4:5]
	v_mov_b32_e32 v7, v3
	v_lshl_add_u64 v[4:5], v[4:5], 0, v[6:7]
	v_lshlrev_b32_e32 v6, 2, v1
	v_lshl_add_u64 v[4:5], v[4:5], 0, v[6:7]
	v_lshlrev_b32_e32 v6, 4, v83
	v_and_b32_e32 v6, 0xf0, v6
	v_readlane_b32 s14, v126, 8
	v_readlane_b32 s15, v126, 9
	v_lshl_add_u64 v[6:7], v[4:5], 0, v[6:7]
	v_lshlrev_b64 v[4:5], 21, v[2:3]
	v_lshl_add_u64 v[4:5], s[14:15], 0, v[4:5]
	v_lshlrev_b32_e32 v2, 11, v1
	v_lshl_add_u64 v[2:3], v[4:5], 0, v[2:3]
	s_mov_b64 s[6:7], 0x10000000
	v_readlane_b32 s9, v126, 3
	v_readlane_b32 s12, v126, 6
	v_readlane_b32 s13, v126, 7
	v_lshl_add_u64 v[66:67], v[2:3], 0, s[6:7]

.LBB0_63:
	s_or_b64 exec, exec, s[0:1]
	v_add_u32_e32 v71, s80, v92
	s_mov_b32 s0, s40
	v_cmp_gt_i32_e64 s[4:5], s0, v71
	s_and_saveexec_b64 s[0:1], s[4:5]
	s_mov_b32 s2, s81
	s_cbranch_execz .LBB0_69
	s_movk_i32 s3, 0x7fff
	v_cmp_lt_i32_e64 s[4:5], s3, v71
	v_lshlrev_b32_e32 v1, 4, v83
	s_and_saveexec_b64 s[6:7], s[4:5]
	s_xor_b64 s[4:5], exec, s[6:7]
	s_cbranch_execz .LBB0_66
	v_add_u32_e32 v0, 0xffff8000, v71
	v_lshrrev_b32_e32 v68, 9, v0
	v_lshlrev_b32_e32 v0, 6, v71
	v_and_b32_e32 v74, 0x3c0, v0
	v_lshlrev_b32_e32 v0, 2, v71
	v_and_b32_e32 v0, 0x7c0, v0
	v_mov_b32_e32 v69, 0
	v_readlane_b32 s8, v126, 2
	v_lshrrev_b32_e32 v71, 4, v83
	v_lshlrev_b64 v[66:67], 23, v[68:69]
	v_readlane_b32 s10, v126, 4
	v_readlane_b32 s11, v126, 5
	v_or_b32_e32 v71, v0, v71
	v_lshlrev_b32_e32 v72, 12, v71
	v_lshl_add_u64 v[66:67], s[10:11], 0, v[66:67]
	v_mov_b32_e32 v73, v69
	v_lshl_add_u64 v[66:67], v[66:67], 0, v[72:73]
	v_lshlrev_b32_e32 v72, 2, v74
	v_lshl_add_u64 v[66:67], v[66:67], 0, v[72:73]
	v_and_b32_e32 v72, 0xf0, v1
	v_readlane_b32 s14, v126, 8
	v_readlane_b32 s15, v126, 9
	v_lshl_add_u64 v[66:67], v[66:67], 0, v[72:73]
	v_lshlrev_b64 v[72:73], 21, v[68:69]
	v_lshl_add_u64 v[72:73], s[14:15], 0, v[72:73]
	v_lshlrev_b32_e32 v68, 11, v74
	v_lshl_add_u64 v[68:69], v[72:73], 0, v[68:69]
	s_mov_b64 s[6:7], 0x10000000
	v_readlane_b32 s9, v126, 3
	v_readlane_b32 s12, v126, 6
	v_readlane_b32 s13, v126, 7
	v_lshl_add_u64 v[74:75], v[68:69], 0, s[6:7]

.LBB0_69:
	s_or_b64 exec, exec, s[0:1]
	s_and_saveexec_b64 s[6:7], vcc
	s_cbranch_execz .LBB0_86
	v_lshlrev_b32_e32 v0, 4, v85
	v_lshrrev_b32_e32 v75, 4, v83
	v_and_b32_e32 v0, 0xf0, v0
	v_add_u32_e32 v0, v84, v0
	v_accvgpr_write_b32 a1, v75
	v_mul_u32_u24_e32 v75, 0x104, v75
	v_add_u32_e32 v75, v0, v75
	v_add_u32_e32 v0, 0x410, v75
	v_accvgpr_write_b32 a3, v0
	v_add_u32_e32 v0, 0x418, v75
	v_accvgpr_write_b32 a5, v0
	v_add_u32_e32 v0, 0x820, v75
	v_accvgpr_write_b32 a7, v0
	v_add_u32_e32 v0, 0x828, v75
	v_accvgpr_write_b32 a9, v0
	v_add_u32_e32 v0, 0xc30, v75
	v_accvgpr_write_b32 a10, v0
	v_add_u32_e32 v0, 0xc38, v75
	v_accvgpr_write_b32 a11, v0
	v_add_u32_e32 v0, 0x1040, v75
	v_accvgpr_write_b32 a12, v0
	v_add_u32_e32 v0, 0x1048, v75
	v_accvgpr_write_b32 a13, v0
	v_add_u32_e32 v0, 0x1450, v75
	v_accvgpr_write_b32 a18, v0
	v_add_u32_e32 v0, 0x1458, v75
	v_accvgpr_write_b32 a19, v0
	v_add_u32_e32 v0, 0x1860, v75
	v_accvgpr_write_b32 a20, v0
	v_add_u32_e32 v0, 0x1868, v75
	v_accvgpr_write_b32 a21, v0
	v_add_u32_e32 v0, 0x1c70, v75
	v_accvgpr_write_b32 a22, v0
	v_add_u32_e32 v0, 0x1c78, v75
	v_accvgpr_write_b32 a23, v0
	v_add_u32_e32 v0, 0x2080, v75
	v_accvgpr_write_b32 a24, v0
	v_add_u32_e32 v0, 0x2088, v75
	v_accvgpr_write_b32 a25, v0
	v_add_u32_e32 v0, 0x2490, v75
	v_accvgpr_write_b32 a30, v0
	v_add_u32_e32 v0, 0x2498, v75
	v_accvgpr_write_b32 a31, v0
	v_add_u32_e32 v0, 0x28a0, v75
	v_accvgpr_write_b32 a32, v0
	v_add_u32_e32 v0, 0x28a8, v75
	v_accvgpr_write_b32 a33, v0
	v_add_u32_e32 v0, 0x2cb0, v75
	v_accvgpr_write_b32 a34, v0
	v_add_u32_e32 v0, 0x2cb8, v75
	v_accvgpr_write_b32 a35, v0
	v_add_u32_e32 v0, 0x30c0, v75
	v_accvgpr_write_b32 a40, v0
	v_add_u32_e32 v0, 0x30c8, v75
	v_lshlrev_b32_e32 v1, 2, v83
	v_accvgpr_write_b32 a41, v0
	v_add_u32_e32 v0, 0x34d0, v75
	v_and_b32_e32 v74, 60, v1
	v_and_b32_e32 v71, 3, v85
	v_accvgpr_write_b32 a42, v0
	v_add_u32_e32 v0, 0x34d8, v75
	v_accvgpr_write_b32 a2, v74
	v_lshrrev_b32_e32 v74, 2, v83
	v_lshlrev_b32_e32 v86, 4, v71
	v_mul_u32_u24_e32 v71, 0x1040, v71
	v_and_b32_e32 v76, 60, v83
	v_accvgpr_write_b32 a43, v0
	v_add_u32_e32 v0, 0x38e0, v75
	v_readlane_b32 s0, v127, 17
	v_add3_u32 v76, v84, v71, v76
	v_or_b32_e32 v84, 16, v74
	v_readlane_b32 s8, v126, 2
	v_accvgpr_write_b32 a44, v0
	v_add_u32_e32 v0, 0x38e8, v75
	s_lshl_b32 s3, s0, 4
	v_accvgpr_write_b32 a4, v84
	v_or_b32_e32 v84, 32, v74
	v_readlane_b32 s14, v126, 8
	v_lshlrev_b32_e32 v71, 2, v82
	v_accvgpr_write_b32 a45, v0
	v_add_u32_e32 v0, 0x3cf0, v75
	v_mov_b32_e32 v1, 0
	v_accvgpr_write_b32 a6, v84
	v_or_b32_e32 v84, 48, v74
	v_readlane_b32 s9, v126, 3
	v_readlane_b32 s10, v126, 4
	v_readlane_b32 s11, v126, 5
	v_readlane_b32 s15, v126, 9
	s_add_u32 s8, s14, 0x10000000
	v_lshlrev_b32_e64 v89, 2, s44
	v_lshlrev_b32_e32 v71, 6, v82
	v_accvgpr_write_b32 a50, v0
	v_add_u32_e32 v0, 0x3cf8, v75
	v_mov_b32_e32 v87, v1
	v_accvgpr_write_b32 a8, v84
	s_addc_u32 s9, s15, 0
	s_mul_i32 s14, s0, 24
	s_mul_i32 s15, s0, 0x60
	s_lshl_b32 s16, s0, 6
	s_mul_i32 s17, s0, 0x600
	v_lshlrev_b32_e64 v71, 6, s44
	s_lshl_b32 s18, s0, 10
	s_mov_b64 s[10:11], 0
	v_accvgpr_write_b32 a51, v0
	s_mov_b32 s19, s40
	s_add_i32 s20, s40, -1
	s_movk_i32 s21, 0x7fff
	s_movk_i32 s22, 0x3fff
	v_mov_b32_e32 v90, v88
	v_mov_b64_e32 v[82:83], v[80:81]
	v_readlane_b32 s12, v126, 6
	v_readlane_b32 s13, v126, 7
	s_waitcnt vmcnt(16)
	s_mov_b32 s39, 0
	s_mov_b32 s38, 0
	s_branch .LBB0_74

.LBB0_86:
	s_or_b64 exec, exec, s[6:7]
	s_cmpk_lg_u32 s80, 0x800
	s_cbranch_scc1 .Lp0dyn_done
	v_readlane_b32 s42, v126, 12
	v_readlane_b32 s43, v126, 13
	v_mov_b32_e32 v0, 0
	v_mov_b32_e32 v1, 1
	s_mov_b64 exec, 1
	s_nop 4
	global_atomic_add v2, v0, v1, s[42:43] offset:4 sc0
	s_waitcnt vmcnt(0)
	v_readfirstlane_b32 s41, v2
	s_mov_b64 exec, -1
	s_cmpk_ge_u32 s41, 0x2800
	s_cbranch_scc1 .Lp0dyn_done
	s_and_b32 s42, s41, 0x7ff
	s_lshr_b32 s41, s41, 11
	s_add_i32 s41, s41, 1
	s_mul_i32 s41, s41, 0x2000
	s_add_i32 s41, s41, s42
	v_mov_b32_e32 v0, s41
	v_accvgpr_write_b32 a1, v0
	v_mov_b32_e32 v85, v77
	v_ashrrev_i32_e32 v82, 6, v85
	v_and_b32_e32 v83, 63, v85
	s_movk_i32 s42, 0x4100
	v_mul_lo_u32 v84, v82, s42
	s_branch .LBB0_57
.Lp0dyn_done:
	v_readlane_b32 s0, v126, 0
	v_readlane_b32 s1, v126, 1
	s_load_dwordx2 s[46:47], s[0:1], 0x120
	s_waitcnt lgkmcnt(0)
	s_cmp_lt_i32 s47, 2
	s_cbranch_scc1 .LBB0_154
	s_waitcnt vmcnt(11)
	v_accvgpr_read_b32 v18, a0
	s_cmp_lt_u32 s47, 20
	s_mov_b64 s[0:1], -1
	s_cbranch_scc0 .LBB0_141
	s_waitcnt vmcnt(0)
	s_barrier
	s_mov_b64 s[4:5], exec
	v_readlane_b32 s0, v126, 10
	v_readlane_b32 s1, v126, 11
	s_and_b64 s[0:1], s[4:5], s[0:1]
	s_mov_b64 exec, s[0:1]
	s_cbranch_execz .LBB0_140
	s_add_i32 s0, 0, 0x23ff0
	v_mov_b32_e32 v0, s0
	s_waitcnt vmcnt(0) expcnt(0) lgkmcnt(0)
	ds_read_b32 v2, v0
	s_add_i32 s0, 0, 0x23ff4
	v_mov_b32_e32 v0, s0
	ds_read_b32 v0, v0
	s_waitcnt lgkmcnt(1)
	v_cmp_ne_u32_e32 vcc, 0, v2
	s_cbranch_vccnz .LBB0_104
	v_readlane_b32 s0, v127, 15
	v_readlane_b32 s1, v127, 16
	v_readlane_b32 s36, v126, 2
	s_load_dwordx2 s[8:9], s[0:1], 0x4
	v_readlane_b32 s42, v126, 8
	v_readlane_b32 s43, v126, 9
	s_add_u32 s0, s42, 0x373e8200
	s_addc_u32 s1, s43, 0
	s_add_u32 s6, s42, 0x373e8400
	s_addc_u32 s7, s43, 0
	v_readlane_b32 s3, v127, 17
	s_waitcnt lgkmcnt(0)
	s_mul_i32 s3, s8, s3
	s_add_u32 s8, s42, 0x373e8500
	s_mul_i32 s3, s3, s9
	s_addc_u32 s9, s43, 0
	s_add_u32 s10, s42, 0x373e8600
	s_addc_u32 s11, s43, 0
	s_add_u32 s12, s42, 0x373e8700
	s_addc_u32 s13, s43, 0
	s_add_u32 s14, s42, 0x373e8800
	s_addc_u32 s15, s43, 0
	s_add_u32 s16, s42, 0x373e8900
	s_addc_u32 s17, s43, 0
	s_add_u32 s18, s42, 0x373e8a00
	s_addc_u32 s19, s43, 0
	s_add_u32 s20, s42, 0x373e8b00
	s_addc_u32 s21, s43, 0
	s_add_u32 s22, s42, 0x373e8c00
	s_addc_u32 s23, s43, 0
	s_add_u32 s24, s42, 0x373e8d00
	s_addc_u32 s25, s43, 0
	s_add_u32 s26, s42, 0x373e8e00
	s_addc_u32 s27, s43, 0
	s_add_u32 s28, s42, 0x373e8f00
	s_addc_u32 s29, s43, 0
	s_add_u32 s30, s42, 0x373e9000
	s_addc_u32 s31, s43, 0
	s_add_u32 s34, s42, 0x373e9100
	s_addc_u32 s35, s43, 0
	v_readlane_b32 s37, v126, 3
	s_add_u32 s36, s42, 0x373e9200
	v_readlane_b32 s38, v126, 4
	s_addc_u32 s37, s43, 0
	v_readlane_b32 s39, v126, 5
	s_add_u32 s38, s42, 0x373e9300
	s_addc_u32 s39, s43, 0
	s_mov_b32 s33, 1
	v_mov_b32_e32 v16, 0
	v_readlane_b32 s40, v126, 6
	v_readlane_b32 s41, v126, 7
	s_branch .LBB0_92

.LBB0_104:
	v_readlane_b32 s8, v126, 12
	v_readlane_b32 s9, v126, 13
	v_readlane_b32 s3, v126, 14
	v_mov_b32_e32 v0, 0
	v_mov_b32_e32 v1, 1
	s_lshl_b32 s3, s3, 8
	s_add_u32 s0, s8, s3
	s_addc_u32 s1, s9, 0
	s_add_u32 s0, s0, 0x1400
	s_addc_u32 s1, s1, 0
	global_atomic_add v4, v0, v1, s[0:1] sc0
	buffer_inv sc1
	v_mov_b32_e32 v5, 0x23ff0
	ds_read2_b32 v[2:3], v5 offset1:1
	s_add_u32 s8, s8, 0x3400
	s_addc_u32 s9, s9, 0
	s_sub_i32 s3, 1, s46
	s_mov_b32 s7, 0
	s_waitcnt lgkmcnt(0)
	v_readfirstlane_b32 s1, v2
	v_readfirstlane_b32 s6, v3
	s_mul_i32 s1, s1, s3
	s_mul_i32 s6, s6, s3
	s_waitcnt vmcnt(1)
	v_readfirstlane_b32 s0, v4
	s_add_i32 s0, s0, 1
	s_cmp_lg_u32 s0, s1
	s_cbranch_scc1 .Lgb0_poll
	buffer_wbl2 sc1
	s_waitcnt vmcnt(0)
	global_atomic_add v0, v1, s[8:9]
.Lgb0_poll:
	global_load_dword v4, v0, s[8:9] sc1
	s_waitcnt vmcnt(0)
	v_readfirstlane_b32 s0, v4
	s_sub_i32 s0, s0, s6
	s_cmp_ge_i32 s0, 0
	s_cbranch_scc1 .Lgb0_rel
	s_add_i32 s7, s7, 1
	s_sleep 1
	s_cmp_lt_u32 s7, 0x40000
	s_cbranch_scc1 .Lgb0_poll
.Lgb0_rel:
.LBB0_140:
	s_or_b64 exec, exec, s[4:5]
	s_mov_b64 s[0:1], 0
	s_waitcnt lgkmcnt(0)
	s_barrier

.Lgb4_poll:
	global_load_dword v4, v0, s[8:9] sc1
	s_waitcnt vmcnt(0)
	v_readfirstlane_b32 s0, v4
	s_sub_i32 s0, s0, s4
	s_cmp_ge_i32 s0, 0
	s_cbranch_scc1 .Lgb4_rel
	s_add_i32 s5, s5, 1
	s_sleep 1
	s_cmp_lt_u32 s5, 0x40000
	s_cbranch_scc1 .Lgb4_poll
